# v44 + attention O stores paired into dwordx4 via v_permlane32_swap (asm guide 7.3)
# baseline (speedup 1.0000x reference)
; __device__ __forceinline__ unsigned cvt_pk_bf16(float lo, float hi) { unsigned r; asm volatile("v_cvt_pk_bf16_f32 %0, %1, %2" : "=v"(r) : "v"(lo), "v"(hi)); return r; }
; template <bool MLA, bool grpB>
; __device__ __forceinline__ void attn_unit_g(LAS unsigned char* lds, const AttnPtrs& P, int b, int h, int qblk) {
;     ...
;     const float ltot = lrun + __shfl_xor(lrun, 32);
;     const float inv = 1.0f / ltot;
;     bf16_t* orow = P.O + (tokb + q0 + r32) * 1024 + h * 128;
; #pragma unroll
;     for (int dvb = 0; dvb < 4; ++dvb)
; #pragma unroll
;         for (int g = 0; g < 4; ++g) { u32x2 w; w.x = pg8::cvt_pk_bf16(o[dvb][4 * g] * inv, o[dvb][4 * g + 1] * inv); w.y = pg8::cvt_pk_bf16(o[dvb][4 * g + 2] * inv, o[dvb][4 * g + 3] * inv);
;             *(u32x2*)(orow + 32 * dvb + 8 * g + 4 * hi) = w; }
.LBB0_1097:
	v_and_b32_e32 v2, 64, v171
	v_xor_b32_e32 v0, 32, v171
	v_add_u32_e32 v2, 64, v2
	v_cmp_lt_i32_e32 vcc, v0, v2
	v_lshlrev_b64 v[2:3], 11, v[160:161]
	v_lshl_add_u64 v[2:3], s[10:11], 0, v[2:3]
	v_cndmask_b32_e32 v0, v171, v0, vcc
	v_lshlrev_b32_e32 v0, 2, v0
	ds_bpermute_b32 v0, v0, v192
	s_mov_b32 s13, s37
	v_lshl_add_u64 v[2:3], v[2:3], 0, s[12:13]
	s_waitcnt lgkmcnt(0)
	v_add_f32_e32 v0, v192, v0
	v_div_scale_f32 v4, s[4:5], v0, v0, 1.0
	v_rcp_f32_e32 v5, v4
	v_div_scale_f32 v6, vcc, 1.0, v0, 1.0
	v_fma_f32 v7, -v4, v5, 1.0
	v_fmac_f32_e32 v5, v7, v5
	v_mul_f32_e32 v7, v6, v5
	v_fma_f32 v8, -v4, v7, v6
	v_fmac_f32_e32 v7, v8, v5
	v_fma_f32 v4, -v4, v7, v6
	v_div_fmas_f32 v4, v4, v5, v7
	v_div_fixup_f32 v4, v4, v0, 1.0
	v_lshlrev_b32_e32 v0, 3, v175
	v_lshl_add_u64 v[98:99], v[2:3], 0, v[0:1]
	v_mul_f32_e32 v0, v64, v4
	v_mul_f32_e32 v2, v65, v4
	v_mul_f32_e32 v3, v67, v4
	v_cvt_pk_bf16_f32 v2, v0, v2
	v_mul_f32_e32 v0, v66, v4
	v_cvt_pk_bf16_f32 v3, v0, v3
	v_mov_b32_e32 v184, v2
	v_mov_b32_e32 v185, v3
	v_mul_f32_e32 v0, v68, v4
	v_mul_f32_e32 v2, v69, v4
	v_mul_f32_e32 v3, v71, v4
	v_cvt_pk_bf16_f32 v2, v0, v2
	v_mul_f32_e32 v0, v70, v4
	v_cvt_pk_bf16_f32 v3, v0, v3
	v_mov_b32_e32 v186, v2
	v_mov_b32_e32 v187, v3
	v_mbcnt_lo_u32_b32 v190, -1, 0
	v_mbcnt_hi_u32_b32 v190, -1, v190
	v_and_b32_e32 v190, 32, v190
	v_lshrrev_b32_e32 v190, 2, v190
	v_mov_b32_e32 v191, 0
	v_lshl_add_u64 v[188:189], v[98:99], 0, v[190:191]
	v_permlane32_swap_b32_e32 v184, v186
	v_permlane32_swap_b32_e32 v185, v187
	flat_store_dwordx4 v[188:189], v[184:187]
	v_mul_f32_e32 v0, v72, v4
	v_mul_f32_e32 v2, v73, v4
	v_mul_f32_e32 v3, v75, v4
	v_cvt_pk_bf16_f32 v2, v0, v2
	v_mul_f32_e32 v0, v74, v4
	v_cvt_pk_bf16_f32 v3, v0, v3
	v_mov_b32_e32 v184, v2
	v_mov_b32_e32 v185, v3
	v_mul_f32_e32 v0, v76, v4
	v_mul_f32_e32 v2, v77, v4
	v_mul_f32_e32 v3, v79, v4
	v_cvt_pk_bf16_f32 v2, v0, v2
	v_mul_f32_e32 v0, v78, v4
	v_cvt_pk_bf16_f32 v3, v0, v3
	v_mov_b32_e32 v186, v2
	v_mov_b32_e32 v187, v3
	s_nop 1
	v_permlane32_swap_b32_e32 v184, v186
	v_permlane32_swap_b32_e32 v185, v187
	flat_store_dwordx4 v[188:189], v[184:187] offset:32
	v_mul_f32_e32 v0, v48, v4
	v_mul_f32_e32 v2, v49, v4
	v_mul_f32_e32 v3, v51, v4
	v_cvt_pk_bf16_f32 v2, v0, v2
	v_mul_f32_e32 v0, v50, v4
	v_cvt_pk_bf16_f32 v3, v0, v3
	v_mov_b32_e32 v184, v2
	v_mov_b32_e32 v185, v3
	v_mul_f32_e32 v0, v52, v4
	v_mul_f32_e32 v2, v53, v4
	v_mul_f32_e32 v3, v55, v4
	v_cvt_pk_bf16_f32 v2, v0, v2
	v_mul_f32_e32 v0, v54, v4
	v_cvt_pk_bf16_f32 v3, v0, v3
	v_mov_b32_e32 v186, v2
	v_mov_b32_e32 v187, v3
	s_nop 1
	v_permlane32_swap_b32_e32 v184, v186
	v_permlane32_swap_b32_e32 v185, v187
	flat_store_dwordx4 v[188:189], v[184:187] offset:64
	v_mul_f32_e32 v0, v56, v4
	v_mul_f32_e32 v2, v57, v4
	v_mul_f32_e32 v3, v59, v4
	v_cvt_pk_bf16_f32 v2, v0, v2
	v_mul_f32_e32 v0, v58, v4
	v_cvt_pk_bf16_f32 v3, v0, v3
	v_mov_b32_e32 v184, v2
	v_mov_b32_e32 v185, v3
	v_mul_f32_e32 v0, v60, v4
	v_mul_f32_e32 v2, v61, v4
	v_mul_f32_e32 v3, v63, v4
	v_cvt_pk_bf16_f32 v2, v0, v2
	v_mul_f32_e32 v0, v62, v4
	v_cvt_pk_bf16_f32 v3, v0, v3
	v_mov_b32_e32 v186, v2
	v_mov_b32_e32 v187, v3
	s_nop 1
	v_permlane32_swap_b32_e32 v184, v186
	v_permlane32_swap_b32_e32 v185, v187
	flat_store_dwordx4 v[188:189], v[184:187] offset:96
	v_mul_f32_e32 v0, v32, v4
	v_mul_f32_e32 v2, v33, v4
	v_mul_f32_e32 v3, v35, v4
	v_cvt_pk_bf16_f32 v2, v0, v2
	v_mul_f32_e32 v0, v34, v4
	v_cvt_pk_bf16_f32 v3, v0, v3
	v_mov_b32_e32 v184, v2
	v_mov_b32_e32 v185, v3
	v_mul_f32_e32 v0, v36, v4
	v_mul_f32_e32 v2, v37, v4
	v_mul_f32_e32 v3, v39, v4
	v_cvt_pk_bf16_f32 v2, v0, v2
	v_mul_f32_e32 v0, v38, v4
	v_cvt_pk_bf16_f32 v3, v0, v3
	v_mov_b32_e32 v186, v2
	v_mov_b32_e32 v187, v3
	s_nop 1
	v_permlane32_swap_b32_e32 v184, v186
	v_permlane32_swap_b32_e32 v185, v187
	flat_store_dwordx4 v[188:189], v[184:187] offset:128
	v_mul_f32_e32 v0, v40, v4
	v_mul_f32_e32 v2, v41, v4
	v_mul_f32_e32 v3, v43, v4
	v_cvt_pk_bf16_f32 v2, v0, v2
	v_mul_f32_e32 v0, v42, v4
	v_cvt_pk_bf16_f32 v3, v0, v3
	v_mov_b32_e32 v184, v2
	v_mov_b32_e32 v185, v3
	v_mul_f32_e32 v0, v44, v4
	v_mul_f32_e32 v2, v45, v4
	v_mul_f32_e32 v3, v47, v4
	v_cvt_pk_bf16_f32 v2, v0, v2
	v_mul_f32_e32 v0, v46, v4
	v_cvt_pk_bf16_f32 v3, v0, v3
	v_mov_b32_e32 v186, v2
	v_mov_b32_e32 v187, v3
	s_nop 1
	v_permlane32_swap_b32_e32 v184, v186
	v_permlane32_swap_b32_e32 v185, v187
	flat_store_dwordx4 v[188:189], v[184:187] offset:160
	v_mul_f32_e32 v0, v16, v4
	v_mul_f32_e32 v2, v17, v4
	v_mul_f32_e32 v3, v19, v4
	v_cvt_pk_bf16_f32 v2, v0, v2
	v_mul_f32_e32 v0, v18, v4
	v_cvt_pk_bf16_f32 v3, v0, v3
	v_mov_b32_e32 v184, v2
	v_mov_b32_e32 v185, v3
	v_mul_f32_e32 v0, v20, v4
	v_mul_f32_e32 v2, v21, v4
	v_mul_f32_e32 v3, v23, v4
	v_cvt_pk_bf16_f32 v2, v0, v2
	v_mul_f32_e32 v0, v22, v4
	v_cvt_pk_bf16_f32 v3, v0, v3
	v_mov_b32_e32 v186, v2
	v_mov_b32_e32 v187, v3
	s_nop 1
	v_permlane32_swap_b32_e32 v184, v186
	v_permlane32_swap_b32_e32 v185, v187
	flat_store_dwordx4 v[188:189], v[184:187] offset:192
	v_mul_f32_e32 v0, v24, v4
	v_mul_f32_e32 v2, v25, v4
	v_mul_f32_e32 v3, v27, v4
	v_cvt_pk_bf16_f32 v2, v0, v2
	v_mul_f32_e32 v0, v26, v4
	v_cvt_pk_bf16_f32 v3, v0, v3
	flat_store_dwordx2 v[98:99], v[2:3] offset:224
	v_mul_f32_e32 v0, v28, v4
	v_mul_f32_e32 v2, v29, v4
	v_mul_f32_e32 v3, v31, v4
	v_cvt_pk_bf16_f32 v2, v0, v2
	v_mul_f32_e32 v0, v30, v4
	v_cvt_pk_bf16_f32 v3, v0, v3

; __device__ __forceinline__ unsigned cvt_pk_bf16(float lo, float hi) { unsigned r; asm volatile("v_cvt_pk_bf16_f32 %0, %1, %2" : "=v"(r) : "v"(lo), "v"(hi)); return r; }
; template <bool MLA, bool grpB>
; __device__ __forceinline__ void attn_unit_g(LAS unsigned char* lds, const AttnPtrs& P, int b, int h, int qblk) {
;     ...
;     const float ltot = lrun + __shfl_xor(lrun, 32);
;     const float inv = 1.0f / ltot;
;     bf16_t* orow = P.O + (tokb + q0 + r32) * 1024 + h * 128;
; #pragma unroll
;     for (int dvb = 0; dvb < 4; ++dvb)
; #pragma unroll
;         for (int g = 0; g < 4; ++g) { u32x2 w; w.x = pg8::cvt_pk_bf16(o[dvb][4 * g] * inv, o[dvb][4 * g + 1] * inv); w.y = pg8::cvt_pk_bf16(o[dvb][4 * g + 2] * inv, o[dvb][4 * g + 3] * inv);
;             *(u32x2*)(orow + 32 * dvb + 8 * g + 4 * hi) = w; }
.LBB0_1166:
	s_nop 2
	v_and_b32_e32 v18, 64, v171
	v_xor_b32_e32 v0, 32, v171
	v_add_u32_e32 v18, 64, v18
	v_cmp_lt_i32_e32 vcc, v0, v18
	v_lshlrev_b64 v[18:19], 11, v[146:147]
	v_lshl_add_u64 v[18:19], s[10:11], 0, v[18:19]
	v_cndmask_b32_e32 v0, v171, v0, vcc
	v_lshlrev_b32_e32 v0, 2, v0
	ds_bpermute_b32 v0, v0, v176
	s_mov_b32 s63, s37
	v_lshl_add_u64 v[18:19], v[18:19], 0, s[62:63]
	s_waitcnt lgkmcnt(0)
	v_add_f32_e32 v0, v176, v0
	v_div_scale_f32 v20, s[4:5], v0, v0, 1.0
	v_rcp_f32_e32 v21, v20
	v_div_scale_f32 v22, vcc, 1.0, v0, 1.0
	v_fma_f32 v23, -v20, v21, 1.0
	v_fmac_f32_e32 v21, v23, v21
	v_mul_f32_e32 v23, v22, v21
	v_fma_f32 v24, -v20, v23, v22
	v_fmac_f32_e32 v23, v24, v21
	v_fma_f32 v20, -v20, v23, v22
	v_div_fmas_f32 v20, v20, v21, v23
	v_div_fixup_f32 v20, v20, v0, 1.0
	v_lshlrev_b32_e32 v0, 3, v159
	v_lshl_add_u64 v[98:99], v[18:19], 0, v[0:1]
	v_mul_f32_e32 v0, v82, v20
	v_mul_f32_e32 v18, v83, v20
	v_cvt_pk_bf16_f32 v18, v0, v18
	v_mul_f32_e32 v0, v84, v20
	v_mul_f32_e32 v19, v85, v20
	v_cvt_pk_bf16_f32 v19, v0, v19
	v_mov_b32_e32 v184, v18
	v_mov_b32_e32 v185, v19
	v_mul_f32_e32 v0, v86, v20
	v_mul_f32_e32 v18, v87, v20
	v_cvt_pk_bf16_f32 v18, v0, v18
	v_mul_f32_e32 v0, v88, v20
	v_mul_f32_e32 v19, v89, v20
	v_cvt_pk_bf16_f32 v19, v0, v19
	v_mov_b32_e32 v186, v18
	v_mov_b32_e32 v187, v19
	v_mbcnt_lo_u32_b32 v190, -1, 0
	v_mbcnt_hi_u32_b32 v190, -1, v190
	v_and_b32_e32 v190, 32, v190
	v_lshrrev_b32_e32 v190, 2, v190
	v_mov_b32_e32 v191, 0
	v_lshl_add_u64 v[188:189], v[98:99], 0, v[190:191]
	v_permlane32_swap_b32_e32 v184, v186
	v_permlane32_swap_b32_e32 v185, v187
	flat_store_dwordx4 v[188:189], v[184:187]
	v_mul_f32_e32 v0, v90, v20
	v_mul_f32_e32 v18, v91, v20
	v_cvt_pk_bf16_f32 v18, v0, v18
	v_mul_f32_e32 v0, v92, v20
	v_mul_f32_e32 v19, v93, v20
	v_cvt_pk_bf16_f32 v19, v0, v19
	v_mov_b32_e32 v184, v18
	v_mov_b32_e32 v185, v19
	v_mul_f32_e32 v0, v94, v20
	v_mul_f32_e32 v18, v95, v20
	v_cvt_pk_bf16_f32 v18, v0, v18
	v_mul_f32_e32 v0, v96, v20
	v_mul_f32_e32 v19, v97, v20
	v_cvt_pk_bf16_f32 v19, v0, v19
	v_mov_b32_e32 v186, v18
	v_mov_b32_e32 v187, v19
	s_nop 1
	v_permlane32_swap_b32_e32 v184, v186
	v_permlane32_swap_b32_e32 v185, v187
	flat_store_dwordx4 v[188:189], v[184:187] offset:32
	v_mul_f32_e32 v0, v66, v20
	v_mul_f32_e32 v18, v67, v20
	v_cvt_pk_bf16_f32 v18, v0, v18
	v_mul_f32_e32 v0, v68, v20
	v_mul_f32_e32 v19, v69, v20
	v_cvt_pk_bf16_f32 v19, v0, v19
	v_mov_b32_e32 v184, v18
	v_mov_b32_e32 v185, v19
	v_mul_f32_e32 v0, v70, v20
	v_mul_f32_e32 v18, v71, v20
	v_cvt_pk_bf16_f32 v18, v0, v18
	v_mul_f32_e32 v0, v72, v20
	v_mul_f32_e32 v19, v73, v20
	v_cvt_pk_bf16_f32 v19, v0, v19
	v_mov_b32_e32 v186, v18
	v_mov_b32_e32 v187, v19
	s_nop 1
	v_permlane32_swap_b32_e32 v184, v186
	v_permlane32_swap_b32_e32 v185, v187
	flat_store_dwordx4 v[188:189], v[184:187] offset:64
	v_mul_f32_e32 v0, v74, v20
	v_mul_f32_e32 v18, v75, v20
	v_cvt_pk_bf16_f32 v18, v0, v18
	v_mul_f32_e32 v0, v76, v20
	v_mul_f32_e32 v19, v77, v20
	v_cvt_pk_bf16_f32 v19, v0, v19
	v_mov_b32_e32 v184, v18
	v_mov_b32_e32 v185, v19
	v_mul_f32_e32 v0, v78, v20
	v_mul_f32_e32 v18, v79, v20
	v_cvt_pk_bf16_f32 v18, v0, v18
	v_mul_f32_e32 v0, v80, v20
	v_mul_f32_e32 v19, v81, v20
	v_cvt_pk_bf16_f32 v19, v0, v19
	v_mov_b32_e32 v186, v18
	v_mov_b32_e32 v187, v19
	s_nop 1
	v_permlane32_swap_b32_e32 v184, v186
	v_permlane32_swap_b32_e32 v185, v187
	flat_store_dwordx4 v[188:189], v[184:187] offset:96
	v_mul_f32_e32 v0, v34, v20
	v_mul_f32_e32 v18, v35, v20
	v_cvt_pk_bf16_f32 v18, v0, v18
	v_mul_f32_e32 v0, v36, v20
	v_mul_f32_e32 v19, v37, v20
	v_cvt_pk_bf16_f32 v19, v0, v19
	v_mov_b32_e32 v184, v18
	v_mov_b32_e32 v185, v19
	v_mul_f32_e32 v0, v38, v20
	v_mul_f32_e32 v18, v39, v20
	v_cvt_pk_bf16_f32 v18, v0, v18
	v_mul_f32_e32 v0, v40, v20
	v_mul_f32_e32 v19, v41, v20
	v_cvt_pk_bf16_f32 v19, v0, v19
	v_mov_b32_e32 v186, v18
	v_mov_b32_e32 v187, v19
	s_nop 1
	v_permlane32_swap_b32_e32 v184, v186
	v_permlane32_swap_b32_e32 v185, v187
	flat_store_dwordx4 v[188:189], v[184:187] offset:128
	v_mul_f32_e32 v0, v42, v20
	v_mul_f32_e32 v18, v43, v20
	v_cvt_pk_bf16_f32 v18, v0, v18
	v_mul_f32_e32 v0, v44, v20
	v_mul_f32_e32 v19, v45, v20
	v_cvt_pk_bf16_f32 v19, v0, v19
	v_mov_b32_e32 v184, v18
	v_mov_b32_e32 v185, v19
	v_mul_f32_e32 v0, v46, v20
	v_mul_f32_e32 v18, v47, v20
	v_cvt_pk_bf16_f32 v18, v0, v18
	v_mul_f32_e32 v0, v48, v20
	v_mul_f32_e32 v19, v49, v20
	v_cvt_pk_bf16_f32 v19, v0, v19
	v_mul_f32_e32 v0, v2, v20
	v_mul_f32_e32 v2, v3, v20
	v_mul_f32_e32 v3, v5, v20
	v_mov_b32_e32 v186, v18
	v_mov_b32_e32 v187, v19
	s_nop 1
	v_permlane32_swap_b32_e32 v184, v186
	v_permlane32_swap_b32_e32 v185, v187
	flat_store_dwordx4 v[188:189], v[184:187] offset:160
	v_cvt_pk_bf16_f32 v2, v0, v2
	v_mul_f32_e32 v0, v4, v20
	v_cvt_pk_bf16_f32 v3, v0, v3
	v_mov_b32_e32 v184, v2
	v_mov_b32_e32 v185, v3
	v_mul_f32_e32 v0, v6, v20
	v_mul_f32_e32 v2, v7, v20
	v_mul_f32_e32 v3, v9, v20
	v_cvt_pk_bf16_f32 v2, v0, v2
	v_mul_f32_e32 v0, v8, v20
	v_cvt_pk_bf16_f32 v3, v0, v3
	v_mov_b32_e32 v186, v2
	v_mov_b32_e32 v187, v3
	s_nop 1
	v_permlane32_swap_b32_e32 v184, v186
	v_permlane32_swap_b32_e32 v185, v187
	flat_store_dwordx4 v[188:189], v[184:187] offset:192
	v_mul_f32_e32 v0, v10, v20
	v_mul_f32_e32 v2, v11, v20
	v_mul_f32_e32 v3, v13, v20
	v_cvt_pk_bf16_f32 v2, v0, v2
	v_mul_f32_e32 v0, v12, v20
	v_cvt_pk_bf16_f32 v3, v0, v3
	flat_store_dwordx2 v[98:99], v[2:3] offset:224
	v_mul_f32_e32 v0, v14, v20
	v_mul_f32_e32 v2, v15, v20
	v_mul_f32_e32 v3, v17, v20
	v_cvt_pk_bf16_f32 v2, v0, v2
	v_mul_f32_e32 v0, v16, v20
	v_cvt_pk_bf16_f32 v3, v0, v3
	s_branch .LBB0_1098

; __device__ __forceinline__ unsigned cvt_pk_bf16(float lo, float hi) { unsigned r; asm volatile("v_cvt_pk_bf16_f32 %0, %1, %2" : "=v"(r) : "v"(lo), "v"(hi)); return r; }
; template <bool MLA, bool grpB>
; __device__ __forceinline__ void attn_unit_g(LAS unsigned char* lds, const AttnPtrs& P, int b, int h, int qblk) {
;     ...
;     const float ltot = lrun + __shfl_xor(lrun, 32);
;     const float inv = 1.0f / ltot;
;     bf16_t* orow = P.O + (tokb + q0 + r32) * 1024 + h * 128;
; #pragma unroll
;     for (int dvb = 0; dvb < 4; ++dvb)
; #pragma unroll
;         for (int g = 0; g < 4; ++g) { u32x2 w; w.x = pg8::cvt_pk_bf16(o[dvb][4 * g] * inv, o[dvb][4 * g + 1] * inv); w.y = pg8::cvt_pk_bf16(o[dvb][4 * g + 2] * inv, o[dvb][4 * g + 3] * inv);
;             *(u32x2*)(orow + 32 * dvb + 8 * g + 4 * hi) = w; }
.LBB0_1224:
	v_and_b32_e32 v2, 64, v171
	v_xor_b32_e32 v0, 32, v171
	v_add_u32_e32 v2, 64, v2
	v_cmp_lt_i32_e32 vcc, v0, v2
	v_lshlrev_b64 v[2:3], 11, v[144:145]
	v_lshl_add_u64 v[2:3], s[62:63], 0, v[2:3]
	v_cndmask_b32_e32 v0, v171, v0, vcc
	v_lshlrev_b32_e32 v0, 2, v0
	ds_bpermute_b32 v0, v0, v180
	s_mov_b32 s71, s65
	v_lshl_add_u64 v[2:3], v[2:3], 0, s[70:71]
	s_waitcnt lgkmcnt(0)
	v_add_f32_e32 v0, v180, v0
	v_div_scale_f32 v4, s[4:5], v0, v0, 1.0
	v_rcp_f32_e32 v5, v4
	v_div_scale_f32 v6, vcc, 1.0, v0, 1.0
	v_fma_f32 v7, -v4, v5, 1.0
	v_fmac_f32_e32 v5, v7, v5
	v_mul_f32_e32 v7, v6, v5
	v_fma_f32 v8, -v4, v7, v6
	v_fmac_f32_e32 v7, v8, v5
	v_fma_f32 v4, -v4, v7, v6
	v_div_fmas_f32 v4, v4, v5, v7
	v_div_fixup_f32 v6, v4, v0, 1.0
	v_lshlrev_b32_e32 v0, 3, v160
	v_lshl_add_u64 v[2:3], v[2:3], 0, v[0:1]
	v_mul_f32_e32 v0, v64, v6
	v_mul_f32_e32 v4, v65, v6
	v_mul_f32_e32 v5, v67, v6
	v_cvt_pk_bf16_f32 v4, v0, v4
	v_mul_f32_e32 v0, v66, v6
	v_cvt_pk_bf16_f32 v5, v0, v5
	v_mov_b32_e32 v184, v4
	v_mov_b32_e32 v185, v5
	v_mul_f32_e32 v0, v68, v6
	v_mul_f32_e32 v4, v69, v6
	v_mul_f32_e32 v5, v71, v6
	v_cvt_pk_bf16_f32 v4, v0, v4
	v_mul_f32_e32 v0, v70, v6
	v_cvt_pk_bf16_f32 v5, v0, v5
	v_mov_b32_e32 v186, v4
	v_mov_b32_e32 v187, v5
	v_mbcnt_lo_u32_b32 v190, -1, 0
	v_mbcnt_hi_u32_b32 v190, -1, v190
	v_and_b32_e32 v190, 32, v190
	v_lshrrev_b32_e32 v190, 2, v190
	v_mov_b32_e32 v191, 0
	v_lshl_add_u64 v[188:189], v[2:3], 0, v[190:191]
	v_permlane32_swap_b32_e32 v184, v186
	v_permlane32_swap_b32_e32 v185, v187
	flat_store_dwordx4 v[188:189], v[184:187]
	v_mul_f32_e32 v0, v72, v6
	v_mul_f32_e32 v4, v73, v6
	v_mul_f32_e32 v5, v75, v6
	v_cvt_pk_bf16_f32 v4, v0, v4
	v_mul_f32_e32 v0, v74, v6
	v_cvt_pk_bf16_f32 v5, v0, v5
	v_mov_b32_e32 v184, v4
	v_mov_b32_e32 v185, v5
	v_mul_f32_e32 v0, v76, v6
	v_mul_f32_e32 v4, v77, v6
	v_mul_f32_e32 v5, v79, v6
	v_cvt_pk_bf16_f32 v4, v0, v4
	v_mul_f32_e32 v0, v78, v6
	v_cvt_pk_bf16_f32 v5, v0, v5
	v_mov_b32_e32 v186, v4
	v_mov_b32_e32 v187, v5
	s_nop 1
	v_permlane32_swap_b32_e32 v184, v186
	v_permlane32_swap_b32_e32 v185, v187
	flat_store_dwordx4 v[188:189], v[184:187] offset:32
	v_mul_f32_e32 v0, v48, v6
	v_mul_f32_e32 v4, v49, v6
	v_mul_f32_e32 v5, v51, v6
	v_cvt_pk_bf16_f32 v4, v0, v4
	v_mul_f32_e32 v0, v50, v6
	v_cvt_pk_bf16_f32 v5, v0, v5
	v_mov_b32_e32 v184, v4
	v_mov_b32_e32 v185, v5
	v_mul_f32_e32 v0, v52, v6
	v_mul_f32_e32 v4, v53, v6
	v_mul_f32_e32 v5, v55, v6
	v_cvt_pk_bf16_f32 v4, v0, v4
	v_mul_f32_e32 v0, v54, v6
	v_cvt_pk_bf16_f32 v5, v0, v5
	v_mov_b32_e32 v186, v4
	v_mov_b32_e32 v187, v5
	s_nop 1
	v_permlane32_swap_b32_e32 v184, v186
	v_permlane32_swap_b32_e32 v185, v187
	flat_store_dwordx4 v[188:189], v[184:187] offset:64
	v_mul_f32_e32 v0, v56, v6
	v_mul_f32_e32 v4, v57, v6
	v_mul_f32_e32 v5, v59, v6
	v_cvt_pk_bf16_f32 v4, v0, v4
	v_mul_f32_e32 v0, v58, v6
	v_cvt_pk_bf16_f32 v5, v0, v5
	v_mov_b32_e32 v184, v4
	v_mov_b32_e32 v185, v5
	v_mul_f32_e32 v0, v60, v6
	v_mul_f32_e32 v4, v61, v6
	v_mul_f32_e32 v5, v63, v6
	v_cvt_pk_bf16_f32 v4, v0, v4
	v_mul_f32_e32 v0, v62, v6
	v_cvt_pk_bf16_f32 v5, v0, v5
	v_mov_b32_e32 v186, v4
	v_mov_b32_e32 v187, v5
	s_nop 1
	v_permlane32_swap_b32_e32 v184, v186
	v_permlane32_swap_b32_e32 v185, v187
	flat_store_dwordx4 v[188:189], v[184:187] offset:96
	v_mul_f32_e32 v0, v32, v6
	v_mul_f32_e32 v4, v33, v6
	v_mul_f32_e32 v5, v35, v6
	v_cvt_pk_bf16_f32 v4, v0, v4
	v_mul_f32_e32 v0, v34, v6
	v_cvt_pk_bf16_f32 v5, v0, v5
	v_mov_b32_e32 v184, v4
	v_mov_b32_e32 v185, v5
	v_mul_f32_e32 v0, v36, v6
	v_mul_f32_e32 v4, v37, v6
	v_mul_f32_e32 v5, v39, v6
	v_cvt_pk_bf16_f32 v4, v0, v4
	v_mul_f32_e32 v0, v38, v6
	v_cvt_pk_bf16_f32 v5, v0, v5
	v_mov_b32_e32 v186, v4
	v_mov_b32_e32 v187, v5
	s_nop 1
	v_permlane32_swap_b32_e32 v184, v186
	v_permlane32_swap_b32_e32 v185, v187
	flat_store_dwordx4 v[188:189], v[184:187] offset:128
	v_mul_f32_e32 v0, v40, v6
	v_mul_f32_e32 v4, v41, v6
	v_mul_f32_e32 v5, v43, v6
	v_cvt_pk_bf16_f32 v4, v0, v4
	v_mul_f32_e32 v0, v42, v6
	v_cvt_pk_bf16_f32 v5, v0, v5
	v_mov_b32_e32 v184, v4
	v_mov_b32_e32 v185, v5
	v_mul_f32_e32 v0, v44, v6
	v_mul_f32_e32 v4, v45, v6
	v_mul_f32_e32 v5, v47, v6
	v_cvt_pk_bf16_f32 v4, v0, v4
	v_mul_f32_e32 v0, v46, v6
	v_cvt_pk_bf16_f32 v5, v0, v5
	v_mov_b32_e32 v186, v4
	v_mov_b32_e32 v187, v5
	s_nop 1
	v_permlane32_swap_b32_e32 v184, v186
	v_permlane32_swap_b32_e32 v185, v187
	flat_store_dwordx4 v[188:189], v[184:187] offset:160
	v_mul_f32_e32 v0, v16, v6
	v_mul_f32_e32 v4, v17, v6
	v_mul_f32_e32 v5, v19, v6
	v_cvt_pk_bf16_f32 v4, v0, v4
	v_mul_f32_e32 v0, v18, v6
	v_cvt_pk_bf16_f32 v5, v0, v5
	v_mov_b32_e32 v184, v4
	v_mov_b32_e32 v185, v5
	v_mul_f32_e32 v0, v20, v6
	v_mul_f32_e32 v4, v21, v6
	v_mul_f32_e32 v5, v23, v6
	v_cvt_pk_bf16_f32 v4, v0, v4
	v_mul_f32_e32 v0, v22, v6
	v_cvt_pk_bf16_f32 v5, v0, v5
	v_mov_b32_e32 v186, v4
	v_mov_b32_e32 v187, v5
	s_nop 1
	v_permlane32_swap_b32_e32 v184, v186
	v_permlane32_swap_b32_e32 v185, v187
	flat_store_dwordx4 v[188:189], v[184:187] offset:192
	v_mul_f32_e32 v0, v24, v6
	v_mul_f32_e32 v4, v25, v6
	v_mul_f32_e32 v5, v27, v6
	v_cvt_pk_bf16_f32 v4, v0, v4
	v_mul_f32_e32 v0, v26, v6
	v_cvt_pk_bf16_f32 v5, v0, v5
	flat_store_dwordx2 v[2:3], v[4:5] offset:224
	v_mul_f32_e32 v0, v28, v6
	v_mul_f32_e32 v4, v29, v6
	v_mul_f32_e32 v5, v31, v6
	v_cvt_pk_bf16_f32 v4, v0, v4
	v_mul_f32_e32 v0, v30, v6
	v_cvt_pk_bf16_f32 v5, v0, v5

; __device__ __forceinline__ unsigned cvt_pk_bf16(float lo, float hi) { unsigned r; asm volatile("v_cvt_pk_bf16_f32 %0, %1, %2" : "=v"(r) : "v"(lo), "v"(hi)); return r; }
; template <bool MLA, bool grpB>
; __device__ __forceinline__ void attn_unit_g(LAS unsigned char* lds, const AttnPtrs& P, int b, int h, int qblk) {
;     ...
;     const float ltot = lrun + __shfl_xor(lrun, 32);
;     const float inv = 1.0f / ltot;
;     bf16_t* orow = P.O + (tokb + q0 + r32) * 1024 + h * 128;
; #pragma unroll
;     for (int dvb = 0; dvb < 4; ++dvb)
; #pragma unroll
;         for (int g = 0; g < 4; ++g) { u32x2 w; w.x = pg8::cvt_pk_bf16(o[dvb][4 * g] * inv, o[dvb][4 * g + 1] * inv); w.y = pg8::cvt_pk_bf16(o[dvb][4 * g + 2] * inv, o[dvb][4 * g + 3] * inv);
;             *(u32x2*)(orow + 32 * dvb + 8 * g + 4 * hi) = w; }
.LBB0_1285:
	v_and_b32_e32 v2, 64, v171
	v_xor_b32_e32 v0, 32, v171
	v_add_u32_e32 v2, 64, v2
	v_cmp_lt_i32_e32 vcc, v0, v2
	v_lshlrev_b64 v[2:3], 11, v[144:145]
	v_lshl_add_u64 v[2:3], s[62:63], 0, v[2:3]
	v_cndmask_b32_e32 v0, v171, v0, vcc
	v_lshlrev_b32_e32 v0, 2, v0
	ds_bpermute_b32 v0, v0, v180
	s_mov_b32 s71, s65
	v_lshl_add_u64 v[2:3], v[2:3], 0, s[70:71]
	s_waitcnt lgkmcnt(0)
	v_add_f32_e32 v0, v180, v0
	v_div_scale_f32 v4, s[4:5], v0, v0, 1.0
	v_rcp_f32_e32 v5, v4
	v_div_scale_f32 v6, vcc, 1.0, v0, 1.0
	s_mov_b64 s[4:5], 0
	v_fma_f32 v7, -v4, v5, 1.0
	v_fmac_f32_e32 v5, v7, v5
	v_mul_f32_e32 v7, v6, v5
	v_fma_f32 v8, -v4, v7, v6
	v_fmac_f32_e32 v7, v8, v5
	v_fma_f32 v4, -v4, v7, v6
	v_div_fmas_f32 v4, v4, v5, v7
	v_div_fixup_f32 v6, v4, v0, 1.0
	v_lshlrev_b32_e32 v0, 3, v160
	v_lshl_add_u64 v[2:3], v[2:3], 0, v[0:1]
	v_mul_f32_e32 v0, v96, v6
	v_mul_f32_e32 v4, v97, v6
	v_mul_f32_e32 v5, v99, v6
	v_cvt_pk_bf16_f32 v4, v0, v4
	v_mul_f32_e32 v0, v98, v6
	v_cvt_pk_bf16_f32 v5, v0, v5
	v_mov_b32_e32 v184, v4
	v_mov_b32_e32 v185, v5
	v_mul_f32_e32 v0, v100, v6
	v_mul_f32_e32 v4, v101, v6
	v_mul_f32_e32 v5, v103, v6
	v_cvt_pk_bf16_f32 v4, v0, v4
	v_mul_f32_e32 v0, v102, v6
	v_cvt_pk_bf16_f32 v5, v0, v5
	v_mov_b32_e32 v186, v4
	v_mov_b32_e32 v187, v5
	v_mbcnt_lo_u32_b32 v190, -1, 0
	v_mbcnt_hi_u32_b32 v190, -1, v190
	v_and_b32_e32 v190, 32, v190
	v_lshrrev_b32_e32 v190, 2, v190
	v_mov_b32_e32 v191, 0
	v_lshl_add_u64 v[188:189], v[2:3], 0, v[190:191]
	v_permlane32_swap_b32_e32 v184, v186
	v_permlane32_swap_b32_e32 v185, v187
	flat_store_dwordx4 v[188:189], v[184:187]
	v_mul_f32_e32 v0, v104, v6
	v_mul_f32_e32 v4, v105, v6
	v_mul_f32_e32 v5, v107, v6
	v_cvt_pk_bf16_f32 v4, v0, v4
	v_mul_f32_e32 v0, v106, v6
	v_cvt_pk_bf16_f32 v5, v0, v5
	v_mov_b32_e32 v184, v4
	v_mov_b32_e32 v185, v5
	v_mul_f32_e32 v0, v108, v6
	v_mul_f32_e32 v4, v109, v6
	v_mul_f32_e32 v5, v111, v6
	v_cvt_pk_bf16_f32 v4, v0, v4
	v_mul_f32_e32 v0, v110, v6
	v_cvt_pk_bf16_f32 v5, v0, v5
	v_mov_b32_e32 v186, v4
	v_mov_b32_e32 v187, v5
	s_nop 1
	v_permlane32_swap_b32_e32 v184, v186
	v_permlane32_swap_b32_e32 v185, v187
	flat_store_dwordx4 v[188:189], v[184:187] offset:32
	v_mul_f32_e32 v0, v80, v6
	v_mul_f32_e32 v4, v81, v6
	v_mul_f32_e32 v5, v83, v6
	v_cvt_pk_bf16_f32 v4, v0, v4
	v_mul_f32_e32 v0, v82, v6
	v_cvt_pk_bf16_f32 v5, v0, v5
	v_mov_b32_e32 v184, v4
	v_mov_b32_e32 v185, v5
	v_mul_f32_e32 v0, v84, v6
	v_mul_f32_e32 v4, v85, v6
	v_mul_f32_e32 v5, v87, v6
	v_cvt_pk_bf16_f32 v4, v0, v4
	v_mul_f32_e32 v0, v86, v6
	v_cvt_pk_bf16_f32 v5, v0, v5
	v_mov_b32_e32 v186, v4
	v_mov_b32_e32 v187, v5
	s_nop 1
	v_permlane32_swap_b32_e32 v184, v186
	v_permlane32_swap_b32_e32 v185, v187
	flat_store_dwordx4 v[188:189], v[184:187] offset:64
	v_mul_f32_e32 v0, v88, v6
	v_mul_f32_e32 v4, v89, v6
	v_mul_f32_e32 v5, v91, v6
	v_cvt_pk_bf16_f32 v4, v0, v4
	v_mul_f32_e32 v0, v90, v6
	v_cvt_pk_bf16_f32 v5, v0, v5
	v_mov_b32_e32 v184, v4
	v_mov_b32_e32 v185, v5
	v_mul_f32_e32 v0, v92, v6
	v_mul_f32_e32 v4, v93, v6
	v_mul_f32_e32 v5, v95, v6
	v_cvt_pk_bf16_f32 v4, v0, v4
	v_mul_f32_e32 v0, v94, v6
	v_cvt_pk_bf16_f32 v5, v0, v5
	v_mov_b32_e32 v186, v4
	v_mov_b32_e32 v187, v5
	s_nop 1
	v_permlane32_swap_b32_e32 v184, v186
	v_permlane32_swap_b32_e32 v185, v187
	flat_store_dwordx4 v[188:189], v[184:187] offset:96
	v_mul_f32_e32 v0, v64, v6
	v_mul_f32_e32 v4, v65, v6
	v_mul_f32_e32 v5, v67, v6
	v_cvt_pk_bf16_f32 v4, v0, v4
	v_mul_f32_e32 v0, v66, v6
	v_cvt_pk_bf16_f32 v5, v0, v5
	v_mov_b32_e32 v184, v4
	v_mov_b32_e32 v185, v5
	v_mul_f32_e32 v0, v68, v6
	v_mul_f32_e32 v4, v69, v6
	v_mul_f32_e32 v5, v71, v6
	v_cvt_pk_bf16_f32 v4, v0, v4
	v_mul_f32_e32 v0, v70, v6
	v_cvt_pk_bf16_f32 v5, v0, v5
	v_mov_b32_e32 v186, v4
	v_mov_b32_e32 v187, v5
	s_nop 1
	v_permlane32_swap_b32_e32 v184, v186
	v_permlane32_swap_b32_e32 v185, v187
	flat_store_dwordx4 v[188:189], v[184:187] offset:128
	v_mul_f32_e32 v0, v72, v6
	v_mul_f32_e32 v4, v73, v6
	v_mul_f32_e32 v5, v75, v6
	v_cvt_pk_bf16_f32 v4, v0, v4
	v_mul_f32_e32 v0, v74, v6
	v_cvt_pk_bf16_f32 v5, v0, v5
	v_mov_b32_e32 v184, v4
	v_mov_b32_e32 v185, v5
	v_mul_f32_e32 v0, v76, v6
	v_mul_f32_e32 v4, v77, v6
	v_mul_f32_e32 v5, v79, v6
	v_cvt_pk_bf16_f32 v4, v0, v4
	v_mul_f32_e32 v0, v78, v6
	v_cvt_pk_bf16_f32 v5, v0, v5
	v_mov_b32_e32 v186, v4
	v_mov_b32_e32 v187, v5
	s_nop 1
	v_permlane32_swap_b32_e32 v184, v186
	v_permlane32_swap_b32_e32 v185, v187
	flat_store_dwordx4 v[188:189], v[184:187] offset:160
	v_mul_f32_e32 v0, v48, v6
	v_mul_f32_e32 v4, v49, v6
	v_mul_f32_e32 v5, v51, v6
	v_cvt_pk_bf16_f32 v4, v0, v4
	v_mul_f32_e32 v0, v50, v6
	v_cvt_pk_bf16_f32 v5, v0, v5
	v_mov_b32_e32 v184, v4
	v_mov_b32_e32 v185, v5
	v_mul_f32_e32 v0, v52, v6
	v_mul_f32_e32 v4, v53, v6
	v_mul_f32_e32 v5, v55, v6
	v_cvt_pk_bf16_f32 v4, v0, v4
	v_mul_f32_e32 v0, v54, v6
	v_cvt_pk_bf16_f32 v5, v0, v5
	v_mov_b32_e32 v186, v4
	v_mov_b32_e32 v187, v5
	s_nop 1
	v_permlane32_swap_b32_e32 v184, v186
	v_permlane32_swap_b32_e32 v185, v187
	flat_store_dwordx4 v[188:189], v[184:187] offset:192
	v_mul_f32_e32 v0, v56, v6
	v_mul_f32_e32 v4, v57, v6
	v_mul_f32_e32 v5, v59, v6
	v_cvt_pk_bf16_f32 v4, v0, v4
	v_mul_f32_e32 v0, v58, v6
	v_cvt_pk_bf16_f32 v5, v0, v5
	flat_store_dwordx2 v[2:3], v[4:5] offset:224
	v_mul_f32_e32 v0, v60, v6
	v_mul_f32_e32 v4, v61, v6
	v_mul_f32_e32 v5, v63, v6
	v_cvt_pk_bf16_f32 v4, v0, v4
	v_mul_f32_e32 v0, v62, v6
	v_cvt_pk_bf16_f32 v5, v0, v5
